# v30 plus static s_setprio 1 for the OLDER half (waves 0-3) in both PEER gather phases (per-half A/B of the priority raise)
# baseline (speedup 1.0000x reference)
; DI int otid_w(int wave) { unsigned z = 0u; asm volatile("" : "+v"(z)); int t = wave * 64 + (int)__builtin_amdgcn_mbcnt_hi(~0u, __builtin_amdgcn_mbcnt_lo(~0u, z)); asm volatile("" : "+v"(t)); return t; }
; #define PEER_META(T, IA, IB, HA, HB) do { const int _t = (T) < TTOK ? (T) : wslot; \
;     IA = *(const u32x4*)(W_IDX(p) + (size_t)_t * 128 + r * 16); IB = *(const u32x4*)(W_IDX(p) + (size_t)_t * 128 + r * 16 + 8); \
;     const u16* _hp = W_H(p) + (size_t)_t * DM + x * 128 + 16 * c; HA = *(const u32x4*)(_hp); HB = *(const u32x4*)(_hp + 8); } while (0)
; #define PEER_GATHER(TAB, IA, IB, RR) do { _Pragma("unroll") for (int g = 0; g < 16; ++g) { \
;     const unsigned _w = (g < 8 ? IA : IB)[(g >> 1) & 3]; RR[g] = *(const u32x4*)((TAB) + row_off(_w, c16, (g & 1) != 0)); } } while (0)
; DI unsigned row_off(unsigned w, unsigned c16, bool hi) {
;   unsigned r; const unsigned m = 128u;
;   if (hi) asm("v_mad_u32_u16 %0, %1, %2, %3 op_sel:[1,0,0,0]" : "=v"(r) : "v"(w), "v"(m), "v"(c16));
;   else asm("v_mad_u32_u16 %0, %1, %2, %3" : "=v"(r) : "v"(w), "v"(m), "v"(c16));
;   return r;
; }
; DI void phase_peer_dots(const Params& p, int layer, int wave) {
;   const int tid = otid_w(wave), lane = tid & 63, wid = wave, c = lane & 7, r = lane >> 3;
;   const int x = blockIdx.x & 7, wslot = (blockIdx.x >> 3) * 8 + wid, nslot = (gridDim.x >> 3) * 8;
;   const unsigned char* ub = W_UB(p) + (size_t)x * (PEER_N * 128);
;   const unsigned c16 = (unsigned)c * 16u;
;   u16* pd = W_Y(p);
;   u32x4 iAa, iBa, iAb, iBb;
;   u32x4 hAa, hBa, hAb, hBb, rrA[16], rrB[16];
;   int xq[4];
;   float xscale;
;     ...
;   int t = wslot;
;   PEER_META(t, iAa, iBa, hAa, hBa);
;   PEER_META(t + nslot, iAb, iBb, hAb, hBb);
;   PEER_GATHER(ub, iAa, iBa, rrA);
.LBB0_125:
	s_and_b64 vcc, exec, s[0:1]
	s_cbranch_vccz .LBB0_133
	s_cmp_gt_i32 s96, 4
	s_mov_b64 s[56:57], -1
	s_cbranch_scc0 .LBB0_133
	s_waitcnt vmcnt(0)
	v_mov_b32_e32 v0, v177
	v_readlane_b32 s0, v253, 51
	v_mbcnt_lo_u32_b32 v0, -1, v0
	v_mbcnt_hi_u32_b32 v0, -1, v0
	v_add_u32_e32 v88, s64, v0
	v_readlane_b32 s1, v253, 52
	v_lshlrev_b32_e32 v0, 1, v88
	v_and_b32_e32 v0, 0x70, v0
	v_lshlrev_b32_e32 v176, 1, v0
	s_waitcnt lgkmcnt(0)
	s_nop 0
	global_load_dwordx4 v[4:7], v176, s[0:1]
	global_load_dwordx4 v[10:13], v176, s[0:1] offset:16
	v_readlane_b32 s0, v253, 56
	v_readlane_b32 s1, v253, 57
	v_and_b32_e32 v89, 7, v88
	s_andn2_b64 vcc, exec, s[0:1]
	v_lshlrev_b32_e32 v160, 4, v89
	s_waitcnt vmcnt(1)
	v_mad_u32_u16 v0, v4, v195, v160
	v_mad_u32_u16 v1, v4, v195, v160 op_sel:[1,0,0,0]
	v_mad_u32_u16 v2, v5, v195, v160
	v_mad_u32_u16 v3, v5, v195, v160 op_sel:[1,0,0,0]
	v_mad_u32_u16 v4, v6, v195, v160
	v_mad_u32_u16 v5, v6, v195, v160 op_sel:[1,0,0,0]
	v_mad_u32_u16 v6, v7, v195, v160
	v_mad_u32_u16 v7, v7, v195, v160 op_sel:[1,0,0,0]
	s_waitcnt vmcnt(0)
	v_mad_u32_u16 v8, v10, v195, v160
	v_mad_u32_u16 v9, v10, v195, v160 op_sel:[1,0,0,0]
	v_mad_u32_u16 v10, v11, v195, v160
	v_mad_u32_u16 v11, v11, v195, v160 op_sel:[1,0,0,0]
	v_mad_u32_u16 v16, v12, v195, v160
	v_mad_u32_u16 v12, v12, v195, v160 op_sel:[1,0,0,0]
	v_mad_u32_u16 v52, v13, v195, v160
	v_mad_u32_u16 v64, v13, v195, v160 op_sel:[1,0,0,0]
	s_cbranch_vccnz .LBB0_132
	global_load_dwordx4 v[12:15], v12, s[14:15]
	s_nop 0
	global_load_dwordx4 v[20:23], v16, s[14:15]
	global_load_dwordx4 v[24:27], v11, s[14:15]
	global_load_dwordx4 v[28:31], v10, s[14:15]
	global_load_dwordx4 v[32:35], v9, s[14:15]
	global_load_dwordx4 v[36:39], v8, s[14:15]
	global_load_dwordx4 v[40:43], v7, s[14:15]
	global_load_dwordx4 v[44:47], v6, s[14:15]
	global_load_dwordx4 v[48:51], v5, s[14:15]
	global_load_dwordx4 v[56:59], v4, s[14:15]
	global_load_dwordx4 v[60:63], v3, s[14:15]
	global_load_dwordx4 v[68:71], v2, s[14:15]
	global_load_dwordx4 v[72:75], v1, s[14:15]
	global_load_dwordx4 v[76:79], v0, s[14:15]
	v_readlane_b32 s0, v253, 60
	v_lshlrev_b32_e32 v90, 1, v160
	v_readlane_b32 s1, v253, 61
	s_nop 4
	global_load_dwordx4 v[0:3], v90, s[0:1] offset:16
	global_load_dwordx4 v[4:7], v90, s[0:1]
	v_readlane_b32 s0, v253, 62
	v_readlane_b32 s1, v253, 63
	s_nop 4
	global_load_dwordx4 v[80:83], v176, s[0:1] offset:16
	global_load_dwordx4 v[84:87], v176, s[0:1]
	v_readlane_b32 s0, v254, 2
	v_readlane_b32 s1, v254, 3
	s_nop 4
	global_load_dwordx4 v[8:11], v90, s[0:1] offset:16
	global_load_dwordx4 v[16:19], v90, s[0:1]
	s_nop 0
	global_load_dwordx4 v[52:55], v52, s[14:15]
	s_nop 0
	global_load_dwordx4 v[64:67], v64, s[14:15]
	v_readlane_b32 s0, v253, 54
	v_mov_b32_e32 v91, v177
	v_readlane_b32 s1, v253, 55
	v_readlane_b32 s12, v254, 4
	v_readlane_b32 s13, v254, 5
	v_lshl_add_u64 v[164:165], s[0:1], 0, v[90:91]
	v_and_b32_e32 v90, 2, v88
	v_cmp_eq_u32_e64 s[4:5], 0, v90
	v_and_b32_e32 v90, 1, v88
	v_lshl_add_u64 v[162:163], s[66:67], 0, v[176:177]
	v_cmp_eq_u32_e64 s[6:7], 0, v90
	v_lshl_add_u64 v[90:91], s[12:13], 0, v[176:177]
	v_lshlrev_b32_e32 v176, 1, v89
	v_lshlrev_b32_e32 v88, 2, v88
	s_movk_i32 s12, 0xe0
	v_lshl_add_u64 v[166:167], v[90:91], 0, v[176:177]
	v_and_or_b32 v176, v88, s12, v176
	v_readlane_b32 s12, v255, 14
	v_readlane_b32 s13, v255, 15
	v_cmp_lt_u32_e64 s[0:1], 3, v89
	s_nop 0
	v_lshl_add_u64 v[168:169], s[12:13], 0, v[176:177]
	s_mov_b32 s12, s38
	v_mbcnt_lo_u32_b32 v230, -1, 0
	v_mbcnt_hi_u32_b32 v230, -1, v230
	v_readlane_b32 s100, v253, 54
	v_readlane_b32 s101, v253, 55
	v_lshlrev_b32_e32 v228, 2, v230
	v_mov_b32_e32 v229, 0
	s_nop 1
	v_lshl_add_u64 v[226:227], s[100:101], 0, v[228:229]
	v_and_b32_e32 v231, 7, v230
	v_lshlrev_b32_e32 v231, 5, v231
	v_and_b32_e32 v230, 56, v230
	v_lshlrev_b32_e32 v230, 2, v230
	v_lshrrev_b32_e32 v228, 2, v160
	v_lshl_add_u64 v[224:225], v[162:163], 0, v[228:229]
	s_waitcnt vmcnt(0)
	v_readlane_b32 s100, v253, 50
	s_nop 3
	s_cmp_ge_u32 s100, 0x100
	s_cbranch_scc1 .Lpeer_prio_d
	s_setprio 1

; DI int otid_w(int wave) { unsigned z = 0u; asm volatile("" : "+v"(z)); int t = wave * 64 + (int)__builtin_amdgcn_mbcnt_hi(~0u, __builtin_amdgcn_mbcnt_lo(~0u, z)); asm volatile("" : "+v"(t)); return t; }
; #define PEER_GATHER(TAB, IA, IB, RR) do { _Pragma("unroll") for (int g = 0; g < 16; ++g) { \
;     const unsigned _w = (g < 8 ? IA : IB)[(g >> 1) & 3]; RR[g] = *(const u32x4*)((TAB) + row_off(_w, c16, (g & 1) != 0)); } } while (0)
; DI void phase_peer_v(const Params& p, int layer, int wave) {
;   const int tid = otid_w(wave), lane = tid & 63, wid = wave, c = lane & 7, r = lane >> 3;
;   const int x = blockIdx.x & 7, wslot = (blockIdx.x >> 3) * 8 + wid, nslot = (gridDim.x >> 3) * 8;
;   const unsigned char* vb = W_VB(p) + (size_t)x * (PEER_N * 128);
;   const unsigned c16 = (unsigned)c * 16u;
;   u16* y2 = W_Y(p);
;   const int ocol = x * 128 + 16 * c + 4 * ((lane >> 4) & 1) + 8 * (lane >> 5);
;   u32x4 iAa, iBa, iAb, iBb;
;   u32x4 wAa, wBa, wAb, wBb, wA, wB;
;   u32x2 hRa, hRb, hR;
;   u32x4 rrA[16], rrB[16];
;     ...
;   int t = wslot;
;   PEER_META_V(t, iAa, iBa, wAa, wBa, hRa);
;   PEER_META_V(t + nslot, iAb, iBb, wAb, wBb, hRb);
;   PEER_GATHER(vb, iAa, iBa, rrA);
.LBB0_184:
	s_and_b64 vcc, exec, s[78:79]
	s_cbranch_vccz .LBB0_195
	s_waitcnt vmcnt(0)
	v_mov_b32_e32 v0, v177
	v_readlane_b32 s0, v253, 51
	v_mbcnt_lo_u32_b32 v0, -1, v0
	v_mbcnt_hi_u32_b32 v0, -1, v0
	v_add_u32_e32 v0, s64, v0
	v_readlane_b32 s1, v253, 52
	v_lshlrev_b32_e32 v1, 1, v0
	v_and_b32_e32 v1, 0x70, v1
	v_lshlrev_b32_e32 v176, 1, v1
	s_waitcnt lgkmcnt(0)
	s_nop 0
	global_load_dwordx4 v[6:9], v176, s[0:1]
	global_load_dwordx4 v[12:15], v176, s[0:1] offset:16
	v_readlane_b32 s0, v253, 56
	v_readlane_b32 s1, v253, 57
	v_lshlrev_b32_e32 v1, 4, v0
	s_andn2_b64 vcc, exec, s[0:1]
	v_and_b32_e32 v205, 0x70, v1
	s_waitcnt vmcnt(1)
	v_mad_u32_u16 v2, v6, v195, v205
	v_mad_u32_u16 v3, v6, v195, v205 op_sel:[1,0,0,0]
	v_mad_u32_u16 v4, v7, v195, v205
	v_mad_u32_u16 v5, v7, v195, v205 op_sel:[1,0,0,0]
	v_mad_u32_u16 v6, v8, v195, v205
	v_mad_u32_u16 v7, v8, v195, v205 op_sel:[1,0,0,0]
	v_mad_u32_u16 v8, v9, v195, v205
	v_mad_u32_u16 v9, v9, v195, v205 op_sel:[1,0,0,0]
	s_waitcnt vmcnt(0)
	v_mad_u32_u16 v10, v12, v195, v205
	v_mad_u32_u16 v11, v12, v195, v205 op_sel:[1,0,0,0]
	v_mad_u32_u16 v16, v13, v195, v205
	v_mad_u32_u16 v17, v13, v195, v205 op_sel:[1,0,0,0]
	v_mad_u32_u16 v18, v14, v195, v205
	v_mad_u32_u16 v19, v14, v195, v205 op_sel:[1,0,0,0]
	v_mad_u32_u16 v12, v15, v195, v205
	v_mad_u32_u16 v1, v15, v195, v205 op_sel:[1,0,0,0]
	s_cbranch_vccnz .LBB0_194
	v_lshrrev_b32_e32 v13, 2, v0
	v_and_b32_e32 v38, 12, v13
	v_readlane_b32 s4, v253, 53
	v_readlane_b32 s0, v254, 28
	v_readlane_b32 s1, v254, 29
	v_or3_b32 v13, v38, s4, v205
	v_lshlrev_b32_e32 v36, 1, v13
	global_load_dwordx4 v[12:15], v12, s[80:81]
	s_nop 0
	global_load_dwordx4 v[20:23], v19, s[80:81]
	global_load_dwordx4 v[24:27], v18, s[80:81]
	global_load_dwordx4 v[28:31], v17, s[80:81]
	global_load_dwordx4 v[32:35], v16, s[80:81]
	global_load_dwordx4 v[40:43], v11, s[80:81]
	global_load_dwordx4 v[52:55], v10, s[80:81]
	global_load_dwordx4 v[60:63], v9, s[80:81]
	global_load_dwordx4 v[68:71], v8, s[80:81]
	global_load_dwordx4 v[80:83], v7, s[80:81]
	global_load_dwordx4 v[88:91], v6, s[80:81]
	global_load_dwordx4 v[96:99], v5, s[80:81]
	global_load_dwordx4 v[104:107], v4, s[80:81]
	global_load_dwordx4 v[112:115], v3, s[80:81]
	global_load_dwordx4 v[120:123], v2, s[80:81]
	v_lshl_add_u64 v[180:181], s[0:1], 0, v[176:177]
	v_readlane_b32 s0, v253, 58
	v_readlane_b32 s1, v253, 59
	v_and_b32_e32 v0, 8, v0
	v_lshl_add_u64 v[178:179], s[66:67], 0, v[176:177]
	v_mov_b32_e32 v37, v177
	v_lshl_add_u64 v[182:183], s[76:77], 0, v[36:37]
	v_lshl_add_u64 v[184:185], s[50:51], 0, v[36:37]
	global_load_dwordx2 v[186:187], v36, s[0:1]
	v_readlane_b32 s0, v254, 26
	v_readlane_b32 s1, v254, 27
	s_nop 4
	global_load_dwordx4 v[8:11], v176, s[0:1] offset:16
	global_load_dwordx4 v[72:75], v176, s[0:1]
	v_readlane_b32 s0, v253, 62
	v_readlane_b32 s1, v253, 63
	s_nop 4
	global_load_dwordx4 v[128:131], v176, s[0:1] offset:16
	global_load_dwordx4 v[140:143], v176, s[0:1]
	v_readlane_b32 s0, v254, 0
	v_readlane_b32 s1, v254, 1
	s_mov_b32 s8, s38
	s_nop 3
	global_load_dwordx2 v[160:161], v36, s[0:1]
	v_readlane_b32 s0, v254, 30
	v_readlane_b32 s1, v254, 31
	s_nop 4
	global_load_dwordx4 v[168:171], v176, s[0:1] offset:16
	global_load_dwordx4 v[172:175], v176, s[0:1]
	global_load_dwordx4 v[16:19], v1, s[80:81]
	v_cmp_eq_u32_e64 s[0:1], 0, v0
	v_add_u32_e32 v0, s4, v205
	v_readlane_b32 s4, v255, 20
	v_add_lshl_u32 v176, v0, v38, 1
	v_readlane_b32 s5, v255, 21
	s_nop 1
	v_lshl_add_u64 v[188:189], s[4:5], 0, v[176:177]
	v_lshrrev_b32_e32 v228, 2, v205
	v_mov_b32_e32 v229, 0
	v_lshl_add_u64 v[224:225], v[178:179], 0, v[228:229]
	v_lshl_add_u64 v[226:227], v[180:181], 0, v[228:229]
	v_mbcnt_lo_u32_b32 v230, -1, 0
	v_mbcnt_hi_u32_b32 v230, -1, v230
	v_and_b32_e32 v230, 56, v230
	v_lshlrev_b32_e32 v230, 2, v230
	s_waitcnt vmcnt(0)
	v_readlane_b32 s100, v253, 50
	s_nop 3
	s_cmp_ge_u32 s100, 0x100
	s_cbranch_scc1 .Lpeer_prio_v
	s_setprio 1
